# stack9 + sample attention online softmax: DPP modifier on v_max itself (wave max 1 instruction per step instead of 4); probe -5 us per P2 pass
# speedup vs baseline: 1.0078x; 1.0036x over previous
; #define DPP_F(old, x, ctrl, rmask, bc) __builtin_bit_cast(float, __builtin_amdgcn_update_dpp(__builtin_bit_cast(int, (old)), __builtin_bit_cast(int, (x)), (ctrl), (rmask), 0xf, (bc)))
; #define LDS_WAIT() asm volatile("s_waitcnt lgkmcnt(0)" ::: "memory")
; __device__ __forceinline__ float wave_max(float v) {
;     v = fmaxf(v, DPP_F(v, v, 0x111, 0xf, false)); v = fmaxf(v, DPP_F(v, v, 0x112, 0xf, false)); v = fmaxf(v, DPP_F(v, v, 0x114, 0xf, false)); v = fmaxf(v, DPP_F(v, v, 0x118, 0xf, false));
;     v = fmaxf(v, DPP_F(v, v, 0x142, 0xa, false)); v = fmaxf(v, DPP_F(v, v, 0x143, 0xc, false));
;     return __builtin_bit_cast(float, __builtin_amdgcn_readlane(__builtin_bit_cast(int, v), 63));
; }
; __device__ __forceinline__ void sattn_unit(const bf16* Qb, const bf16* Kb, const bf16* Vb, const float* ck, const float* cv, const int* pt, bf16* MIX, const float* sg, float lam,
;                                            int s, int h, int c0, LAS unsigned char* lds, int tid_in) {
;     ...
;         for (int c = 0; c < 8; ++c) { const int t = c & 3;
;             const float sv = sc[c * 64 + lane] - slope2 * (float)(PAST + t - (kp0 + lane));
;             const float mn = __builtin_bit_cast(float, __builtin_amdgcn_readfirstlane(__builtin_bit_cast(int, fmaxf(mrun[c], wave_max(sv))))); const float p = __builtin_amdgcn_exp2f(sv - mn);
;             const float fsc_ = __builtin_amdgcn_exp2f(mrun[c] - mn); lrun[c] = __builtin_bit_cast(float, __builtin_amdgcn_readfirstlane(__builtin_bit_cast(int, lrun[c] * fsc_ + wave_sum(p)))); mrun[c] = mn; pl[lane * 8 + c] = p; acc[c][0] *= fsc_; acc[c][1] *= fsc_; acc[c][2] *= fsc_; acc[c][3] *= fsc_; }
;         LDS_WAIT(); asm volatile("" ::: "memory");
;         const float* vp = cv + ((tok0 + hi) * NH + h) * 128 + 4 * r32;
; #pragma unroll 1
;         for (int k0 = 0; k0 < 64; k0 += 32) { f32x4 vv[16];
; #pragma unroll
;             for (int k = 0; k < 16; ++k) vv[k] = *(const f32x4*)(vp + (size_t)(k0 + 2 * k) * NH * 128);
.LBB0_498:
	s_or_b64 exec, exec, s[0:1]
	s_waitcnt lgkmcnt(0)
	s_nop 8
	v_or_b32_e32 v213, s23, v150
	ds_read2st64_b32 v[210:211], v152 offset1:1
	v_sub_u32_e32 v212, 0x800, v213
	v_cvt_f32_u32_e32 v216, v212
	v_mov_b32_e32 v217, 0
	v_mov_b32_e32 v218, 0
	v_mov_b32_e32 v221, 0
	s_waitcnt lgkmcnt(0)
	v_fma_f32 v210, -v151, v216, v210
	v_mov_b32_e32 v212, v210
	v_or_b32_e32 v122, v128, v134
	v_lshlrev_b64 v[240:241], 11, v[122:123]
	v_lshl_add_u64 v[146:147], v[142:143], 0, v[240:241]
	v_mov_b32_e32 v106, v146
	v_mov_b32_e32 v107, v147
	s_movk_i32 s0, 0x2000
	v_add_co_u32_e64 v2, s[0:1], s0, v106
	global_load_dwordx4 v[110:113], v[106:107], off
	s_nop 0
	v_addc_co_u32_e64 v3, s[0:1], 0, v107, s[0:1]
	s_movk_i32 s0, 0x4000
	global_load_dwordx4 v[114:117], v[2:3], off offset:-4096
	global_load_dwordx4 v[118:121], v[2:3], off
	v_add_co_u32_e64 v2, s[0:1], s0, v106
	s_nop 0
	s_nop 0
	v_addc_co_u32_e64 v3, s[0:1], 0, v107, s[0:1]
	global_load_dwordx4 v[122:125], v[2:3], off offset:-4096
	global_load_dwordx4 v[126:129], v[2:3], off
	s_movk_i32 s0, 0x6000
	v_add_co_u32_e64 v6, s[0:1], s0, v106
	s_nop 0
	s_nop 0
	v_addc_co_u32_e64 v7, s[0:1], 0, v107, s[0:1]
	s_mov_b32 s0, 0x8000
	s_nop 0
	v_add_co_u32_e64 v14, s[0:1], s0, v106
	global_load_dwordx4 v[2:5], v[6:7], off offset:-4096
	s_nop 0
	global_load_dwordx4 v[6:9], v[6:7], off
	v_addc_co_u32_e64 v15, s[0:1], 0, v107, s[0:1]
	s_mov_b32 s0, 0xa000
	s_nop 0
	v_add_co_u32_e64 v248, s[0:1], s0, v106
	global_load_dwordx4 v[10:13], v[14:15], off offset:-4096
	s_nop 0
	global_load_dwordx4 v[14:17], v[14:15], off
	v_addc_co_u32_e64 v249, s[0:1], 0, v107, s[0:1]
	s_mov_b32 s0, 0xc000
	s_nop 0
	v_add_co_u32_e64 v94, s[0:1], s0, v106
	global_load_dwordx4 v[242:245], v[248:249], off offset:-4096
	s_nop 0
	global_load_dwordx4 v[248:251], v[248:249], off
	v_addc_co_u32_e64 v95, s[0:1], 0, v107, s[0:1]
	s_mov_b32 s0, 0xe000
	s_nop 0
	v_add_co_u32_e64 v102, s[0:1], s0, v106
	global_load_dwordx4 v[90:93], v[94:95], off offset:-4096
	s_nop 0
	global_load_dwordx4 v[94:97], v[94:95], off
	v_addc_co_u32_e64 v103, s[0:1], 0, v107, s[0:1]
	s_mov_b32 s0, 0xf000
	s_nop 0
	v_add_co_u32_e64 v106, s[0:1], s0, v106
	global_load_dwordx4 v[98:101], v[102:103], off offset:-4096
	s_nop 0
	global_load_dwordx4 v[102:105], v[102:103], off
	v_addc_co_u32_e64 v107, s[0:1], 0, v107, s[0:1]
	global_load_dwordx4 v[106:109], v[106:107], off
	v_mov_b32_e32 v154, 0
	v_max_f32_dpp v212, v210, v210 row_shr:1 row_mask:0xf bank_mask:0xf
	v_mov_b32_e32 v156, 0
	v_mov_b32_e32 v158, 0
	v_max_f32_dpp v212, v212, v212 row_shr:2 row_mask:0xf bank_mask:0xf
	v_mov_b32_e32 v160, 0
	v_mov_b32_e32 v162, 0
	v_max_f32_dpp v212, v212, v212 row_shr:4 row_mask:0xf bank_mask:0xf
	v_mov_b32_e32 v164, 0
	v_mov_b32_e32 v166, 0
	v_max_f32_dpp v212, v212, v212 row_shr:8 row_mask:0xf bank_mask:0xf
	v_mov_b32_e32 v168, 0
	s_mov_b32 s46, 0
	v_max_f32_dpp v212, v212, v212 row_bcast:15 row_mask:0xa bank_mask:0xf
	s_nop 1
	v_max_f32_dpp v212, v212, v212 row_bcast:31 row_mask:0xc bank_mask:0xf
	v_max_f32_e64 v214, s25, s25
	v_readlane_b32 s0, v212, 63
	s_nop 1
	v_max_f32_e64 v212, s0, s0
	v_max_f32_e32 v212, v214, v212
	s_nop 0
	v_readfirstlane_b32 s23, v212
	s_nop 1
	v_subrev_f32_e32 v210, s23, v210
	v_exp_f32_e32 v210, v210
	v_mov_b32_e32 v212, s23
	v_sub_f32_e32 v212, s25, v212
	v_exp_f32_e32 v212, v212
	v_add_f32_dpp v215, v210, v210 row_shr:1 row_mask:0xf bank_mask:0xf bound_ctrl:1
	v_mul_f32_e32 v214, v86, v212
	s_nop 0
	v_add_f32_dpp v215, v215, v215 row_shr:2 row_mask:0xf bank_mask:0xf bound_ctrl:1
	v_pk_mul_f32 v[50:51], v[50:51], v[212:213] op_sel_hi:[1,0]
	v_pk_mul_f32 v[52:53], v[52:53], v[212:213] op_sel_hi:[1,0]
	v_add_f32_dpp v215, v215, v215 row_shr:4 row_mask:0xf bank_mask:0xf bound_ctrl:1
	v_sub_u32_e32 v212, 0x801, v213
	v_readfirstlane_b32 s25, v214
	v_add_f32_dpp v215, v215, v215 row_shr:8 row_mask:0xf bank_mask:0xf bound_ctrl:1
	s_nop 1
	v_mov_b32_dpp v217, v215 row_bcast:15 row_mask:0xa bank_mask:0xf
	v_add_f32_e32 v153, v215, v217
	v_cvt_f32_u32_e32 v217, v212
	v_fma_f32 v211, -v151, v217, v211
	v_mov_b32_e32 v212, v211
	v_mov_b32_dpp v154, v153 row_bcast:31 row_mask:0xc bank_mask:0xf
	s_nop 0
	v_max_f32_dpp v212, v211, v211 row_shr:1 row_mask:0xf bank_mask:0xf
	s_nop 1
	v_max_f32_dpp v212, v212, v212 row_shr:2 row_mask:0xf bank_mask:0xf
	s_nop 1
	v_max_f32_dpp v212, v212, v212 row_shr:4 row_mask:0xf bank_mask:0xf
	s_nop 1
	v_max_f32_dpp v212, v212, v212 row_shr:8 row_mask:0xf bank_mask:0xf
	s_nop 1
	v_max_f32_dpp v212, v212, v212 row_bcast:15 row_mask:0xa bank_mask:0xf
	s_nop 1
	v_max_f32_dpp v212, v212, v212 row_bcast:31 row_mask:0xc bank_mask:0xf
	v_max_f32_e64 v214, s26, s26
	v_readlane_b32 s0, v212, 63
	s_nop 1
	v_max_f32_e64 v212, s0, s0
	v_max_f32_e32 v212, v214, v212
	s_nop 0
	v_readfirstlane_b32 s24, v212
	s_nop 1
	v_subrev_f32_e32 v211, s24, v211
	v_exp_f32_e32 v211, v211
	v_mov_b32_e32 v212, s24
	v_sub_f32_e32 v212, s26, v212
	v_exp_f32_e32 v212, v212
	v_add_f32_dpp v215, v211, v211 row_shr:1 row_mask:0xf bank_mask:0xf bound_ctrl:1
	v_mul_f32_e32 v214, v87, v212
	s_nop 0
	v_add_f32_dpp v215, v215, v215 row_shr:2 row_mask:0xf bank_mask:0xf bound_ctrl:1
	v_pk_mul_f32 v[58:59], v[58:59], v[212:213] op_sel_hi:[1,0]
	v_pk_mul_f32 v[60:61], v[60:61], v[212:213] op_sel_hi:[1,0]
	v_add_f32_dpp v215, v215, v215 row_shr:4 row_mask:0xf bank_mask:0xf bound_ctrl:1
	v_sub_u32_e32 v212, 0x802, v213
	v_readfirstlane_b32 s26, v214
	v_add_f32_dpp v215, v215, v215 row_shr:8 row_mask:0xf bank_mask:0xf bound_ctrl:1
	v_sub_u32_e32 v213, 0x803, v213
	s_nop 0
	v_mov_b32_dpp v218, v215 row_bcast:15 row_mask:0xa bank_mask:0xf
	v_add_f32_e32 v155, v215, v218
	ds_read2st64_b32 v[218:219], v152 offset0:2 offset1:3
	v_cvt_f32_u32_e32 v215, v212
	v_mov_b32_dpp v156, v155 row_bcast:31 row_mask:0xc bank_mask:0xf
	s_waitcnt lgkmcnt(0)
; #define DPP_F(old, x, ctrl, rmask, bc) __builtin_bit_cast(float, __builtin_amdgcn_update_dpp(__builtin_bit_cast(int, (old)), __builtin_bit_cast(int, (x)), (ctrl), (rmask), 0xf, (bc)))
; __device__ __forceinline__ float wave_max(float v) {
;     v = fmaxf(v, DPP_F(v, v, 0x111, 0xf, false)); v = fmaxf(v, DPP_F(v, v, 0x112, 0xf, false)); v = fmaxf(v, DPP_F(v, v, 0x114, 0xf, false)); v = fmaxf(v, DPP_F(v, v, 0x118, 0xf, false));
;     v = fmaxf(v, DPP_F(v, v, 0x142, 0xa, false)); v = fmaxf(v, DPP_F(v, v, 0x143, 0xc, false));
;     return __builtin_bit_cast(float, __builtin_amdgcn_readlane(__builtin_bit_cast(int, v), 63));
; }
; __device__ __forceinline__ void sattn_unit(const bf16* Qb, const bf16* Kb, const bf16* Vb, const float* ck, const float* cv, const int* pt, bf16* MIX, const float* sg, float lam,
;                                            int s, int h, int c0, LAS unsigned char* lds, int tid_in) {
;     ...
;         for (int c = 0; c < 8; ++c) { const int t = c & 3;
;             const float sv = sc[c * 64 + lane] - slope2 * (float)(PAST + t - (kp0 + lane));
;             const float mn = __builtin_bit_cast(float, __builtin_amdgcn_readfirstlane(__builtin_bit_cast(int, fmaxf(mrun[c], wave_max(sv))))); const float p = __builtin_amdgcn_exp2f(sv - mn);
;             const float fsc_ = __builtin_amdgcn_exp2f(mrun[c] - mn); lrun[c] = __builtin_bit_cast(float, __builtin_amdgcn_readfirstlane(__builtin_bit_cast(int, lrun[c] * fsc_ + wave_sum(p)))); mrun[c] = mn; pl[lane * 8 + c] = p; acc[c][0] *= fsc_; acc[c][1] *= fsc_; acc[c][2] *= fsc_; acc[c][3] *= fsc_; }
	v_fma_f32 v212, -v151, v215, v218
	v_mov_b32_e32 v214, v212
	s_nop 1
	v_max_f32_dpp v214, v212, v212 row_shr:1 row_mask:0xf bank_mask:0xf
	s_nop 1
	v_max_f32_dpp v214, v214, v214 row_shr:2 row_mask:0xf bank_mask:0xf
	s_nop 1
	v_max_f32_dpp v214, v214, v214 row_shr:4 row_mask:0xf bank_mask:0xf
	s_nop 1
	v_max_f32_dpp v214, v214, v214 row_shr:8 row_mask:0xf bank_mask:0xf
	s_nop 1
	v_max_f32_dpp v214, v214, v214 row_bcast:15 row_mask:0xa bank_mask:0xf
	s_nop 1
	v_max_f32_dpp v214, v214, v214 row_bcast:31 row_mask:0xc bank_mask:0xf
	v_max_f32_e64 v218, s29, s29
	v_readlane_b32 s0, v214, 63
	s_nop 1
	v_max_f32_e64 v214, s0, s0
	v_max_f32_e32 v214, v218, v214
	s_nop 0
	v_readfirstlane_b32 s27, v214
	s_nop 1
	v_mov_b32_e32 v214, s27
	v_sub_f32_e32 v214, s29, v214
	v_exp_f32_e32 v214, v214
	v_subrev_f32_e32 v212, s27, v212
	v_exp_f32_e32 v212, v212
	v_mul_f32_e32 v218, v88, v214
	v_pk_mul_f32 v[66:67], v[66:67], v[214:215] op_sel_hi:[1,0]
	v_pk_mul_f32 v[68:69], v[68:69], v[214:215] op_sel_hi:[1,0]
	v_cvt_f32_u32_e32 v214, v213
	v_readfirstlane_b32 s29, v218
	v_add_f32_dpp v220, v212, v212 row_shr:1 row_mask:0xf bank_mask:0xf bound_ctrl:1
	v_fma_f32 v213, -v151, v214, v219
	v_mov_b32_e32 v218, v213
	v_add_f32_dpp v220, v220, v220 row_shr:2 row_mask:0xf bank_mask:0xf bound_ctrl:1
	s_nop 0
	v_max_f32_dpp v218, v213, v213 row_shr:1 row_mask:0xf bank_mask:0xf
	v_add_f32_dpp v220, v220, v220 row_shr:4 row_mask:0xf bank_mask:0xf bound_ctrl:1
	s_nop 0
	v_max_f32_dpp v218, v218, v218 row_shr:2 row_mask:0xf bank_mask:0xf
	v_add_f32_dpp v220, v220, v220 row_shr:8 row_mask:0xf bank_mask:0xf bound_ctrl:1
	s_nop 0
	v_max_f32_dpp v218, v218, v218 row_shr:4 row_mask:0xf bank_mask:0xf
	v_mov_b32_dpp v221, v220 row_bcast:15 row_mask:0xa bank_mask:0xf
	v_add_f32_e32 v157, v220, v221
	v_max_f32_dpp v218, v218, v218 row_shr:8 row_mask:0xf bank_mask:0xf
	v_mov_b32_e32 v221, 0
	v_mov_b32_dpp v158, v157 row_bcast:31 row_mask:0xc bank_mask:0xf
	v_max_f32_dpp v218, v218, v218 row_bcast:15 row_mask:0xa bank_mask:0xf
	s_nop 1
	v_max_f32_dpp v218, v218, v218 row_bcast:31 row_mask:0xc bank_mask:0xf
	v_max_f32_e64 v219, s30, s30
	v_readlane_b32 s0, v218, 63
	s_nop 1
	v_max_f32_e64 v218, s0, s0
	v_max_f32_e32 v218, v219, v218
	s_nop 0
	v_readfirstlane_b32 s28, v218
	s_nop 1
	v_subrev_f32_e32 v213, s28, v213
	v_exp_f32_e32 v213, v213
	v_mov_b32_e32 v218, s28
	v_sub_f32_e32 v218, s30, v218
	v_exp_f32_e32 v218, v218
	ds_write_b128 v137, v[210:213] offset:16384
	ds_read2st64_b32 v[210:211], v152 offset0:4 offset1:5
	v_add_f32_dpp v220, v213, v213 row_shr:1 row_mask:0xf bank_mask:0xf bound_ctrl:1
	v_mul_f32_e32 v219, v89, v218
	v_pk_mul_f32 v[78:79], v[78:79], v[218:219] op_sel_hi:[1,0]
	v_pk_mul_f32 v[80:81], v[80:81], v[218:219] op_sel_hi:[1,0]
	s_waitcnt lgkmcnt(0)
	v_fma_f32 v210, -v151, v216, v210
	v_mov_b32_e32 v212, v210
	v_fma_f32 v211, -v151, v217, v211
	v_mov_b32_e32 v218, 0
	v_max_f32_dpp v212, v210, v210 row_shr:1 row_mask:0xf bank_mask:0xf
	v_mov_b32_e32 v217, 0
	v_add_f32_dpp v220, v220, v220 row_shr:2 row_mask:0xf bank_mask:0xf bound_ctrl:1
	v_max_f32_dpp v212, v212, v212 row_shr:2 row_mask:0xf bank_mask:0xf
	s_nop 0
	v_add_f32_dpp v220, v220, v220 row_shr:4 row_mask:0xf bank_mask:0xf bound_ctrl:1
	v_readfirstlane_b32 s30, v219
	v_max_f32_dpp v212, v212, v212 row_shr:4 row_mask:0xf bank_mask:0xf
	v_add_f32_dpp v220, v220, v220 row_shr:8 row_mask:0xf bank_mask:0xf bound_ctrl:1
	s_nop 0
	v_max_f32_dpp v212, v212, v212 row_shr:8 row_mask:0xf bank_mask:0xf
	v_mov_b32_dpp v221, v220 row_bcast:15 row_mask:0xa bank_mask:0xf
	v_add_f32_e32 v159, v220, v221
	v_max_f32_dpp v212, v212, v212 row_bcast:15 row_mask:0xa bank_mask:0xf
	s_nop 0
	v_mov_b32_dpp v160, v159 row_bcast:31 row_mask:0xc bank_mask:0xf
	s_nop 0
	v_max_f32_dpp v212, v212, v212 row_bcast:31 row_mask:0xc bank_mask:0xf
	v_max_f32_e64 v213, s35, s35
	v_readlane_b32 s0, v212, 63
	s_nop 1
	v_max_f32_e64 v212, s0, s0
	v_max_f32_e32 v212, v213, v212
	s_nop 0
	v_readfirstlane_b32 s31, v212
	s_nop 1
	v_mov_b32_e32 v212, s31
	v_sub_f32_e32 v212, s35, v212
	v_exp_f32_e32 v212, v212
	v_subrev_f32_e32 v210, s31, v210
	v_exp_f32_e32 v210, v210
	v_mul_f32_e32 v213, v82, v212
	v_pk_mul_f32 v[54:55], v[54:55], v[212:213] op_sel_hi:[1,0]
	v_pk_mul_f32 v[56:57], v[56:57], v[212:213] op_sel_hi:[1,0]
	v_mov_b32_e32 v212, v211
	v_readfirstlane_b32 s35, v213
	v_add_f32_dpp v216, v210, v210 row_shr:1 row_mask:0xf bank_mask:0xf bound_ctrl:1
	v_max_f32_dpp v212, v211, v211 row_shr:1 row_mask:0xf bank_mask:0xf
	s_nop 0
	v_add_f32_dpp v216, v216, v216 row_shr:2 row_mask:0xf bank_mask:0xf bound_ctrl:1
	s_nop 0
	v_max_f32_dpp v212, v212, v212 row_shr:2 row_mask:0xf bank_mask:0xf
	v_add_f32_dpp v216, v216, v216 row_shr:4 row_mask:0xf bank_mask:0xf bound_ctrl:1
	s_nop 0
	v_max_f32_dpp v212, v212, v212 row_shr:4 row_mask:0xf bank_mask:0xf
	v_add_f32_dpp v216, v216, v216 row_shr:8 row_mask:0xf bank_mask:0xf bound_ctrl:1
	s_nop 0
	v_max_f32_dpp v212, v212, v212 row_shr:8 row_mask:0xf bank_mask:0xf
	v_mov_b32_dpp v218, v216 row_bcast:15 row_mask:0xa bank_mask:0xf
	v_add_f32_e32 v161, v216, v218
	v_max_f32_dpp v212, v212, v212 row_bcast:15 row_mask:0xa bank_mask:0xf
	v_mov_b32_e32 v218, 0
	v_mov_b32_dpp v162, v161 row_bcast:31 row_mask:0xc bank_mask:0xf
	v_max_f32_dpp v212, v212, v212 row_bcast:31 row_mask:0xc bank_mask:0xf
	v_max_f32_e64 v213, s42, s42
	v_readlane_b32 s0, v212, 63
	s_nop 1
	v_max_f32_e64 v212, s0, s0
	v_max_f32_e32 v212, v213, v212
	s_nop 0
	v_readfirstlane_b32 s34, v212
	s_nop 1
	v_mov_b32_e32 v212, s34
	v_sub_f32_e32 v212, s42, v212
	v_exp_f32_e32 v212, v212
	v_subrev_f32_e32 v211, s34, v211
	v_exp_f32_e32 v211, v211
	v_mul_f32_e32 v213, v83, v212
	s_nop 0
	v_readfirstlane_b32 s42, v213
	v_pk_mul_f32 v[62:63], v[62:63], v[212:213] op_sel_hi:[1,0]
	v_pk_mul_f32 v[64:65], v[64:65], v[212:213] op_sel_hi:[1,0]
	ds_read2st64_b32 v[212:213], v152 offset0:6 offset1:7
	v_add_f32_dpp v216, v211, v211 row_shr:1 row_mask:0xf bank_mask:0xf bound_ctrl:1
	s_waitcnt lgkmcnt(0)
; #define DPP_F(old, x, ctrl, rmask, bc) __builtin_bit_cast(float, __builtin_amdgcn_update_dpp(__builtin_bit_cast(int, (old)), __builtin_bit_cast(int, (x)), (ctrl), (rmask), 0xf, (bc)))
; __device__ __forceinline__ float wave_max(float v) {
;     v = fmaxf(v, DPP_F(v, v, 0x111, 0xf, false)); v = fmaxf(v, DPP_F(v, v, 0x112, 0xf, false)); v = fmaxf(v, DPP_F(v, v, 0x114, 0xf, false)); v = fmaxf(v, DPP_F(v, v, 0x118, 0xf, false));
;     v = fmaxf(v, DPP_F(v, v, 0x142, 0xa, false)); v = fmaxf(v, DPP_F(v, v, 0x143, 0xc, false));
;     return __builtin_bit_cast(float, __builtin_amdgcn_readlane(__builtin_bit_cast(int, v), 63));
; }
; __device__ __forceinline__ void sattn_unit(const bf16* Qb, const bf16* Kb, const bf16* Vb, const float* ck, const float* cv, const int* pt, bf16* MIX, const float* sg, float lam,
;                                            int s, int h, int c0, LAS unsigned char* lds, int tid_in) {
;     ...
;         for (int c = 0; c < 8; ++c) { const int t = c & 3;
;             const float sv = sc[c * 64 + lane] - slope2 * (float)(PAST + t - (kp0 + lane));
;             const float mn = __builtin_bit_cast(float, __builtin_amdgcn_readfirstlane(__builtin_bit_cast(int, fmaxf(mrun[c], wave_max(sv))))); const float p = __builtin_amdgcn_exp2f(sv - mn);
;             const float fsc_ = __builtin_amdgcn_exp2f(mrun[c] - mn); lrun[c] = __builtin_bit_cast(float, __builtin_amdgcn_readfirstlane(__builtin_bit_cast(int, lrun[c] * fsc_ + wave_sum(p)))); mrun[c] = mn; pl[lane * 8 + c] = p; acc[c][0] *= fsc_; acc[c][1] *= fsc_; acc[c][2] *= fsc_; acc[c][3] *= fsc_; }
	v_fma_f32 v212, -v151, v215, v212
	v_add_f32_dpp v216, v216, v216 row_shr:2 row_mask:0xf bank_mask:0xf bound_ctrl:1
	v_mov_b32_e32 v215, v212
	v_fma_f32 v213, -v151, v214, v213
	v_add_f32_dpp v216, v216, v216 row_shr:4 row_mask:0xf bank_mask:0xf bound_ctrl:1
	s_nop 1
	v_add_f32_dpp v216, v216, v216 row_shr:8 row_mask:0xf bank_mask:0xf bound_ctrl:1
	v_max_f32_dpp v215, v212, v212 row_shr:1 row_mask:0xf bank_mask:0xf
	v_mov_b32_e32 v214, v213
	v_mov_b32_dpp v217, v216 row_bcast:15 row_mask:0xa bank_mask:0xf
	v_add_f32_e32 v163, v216, v217
	v_max_f32_dpp v215, v215, v215 row_shr:2 row_mask:0xf bank_mask:0xf
	v_max_f32_dpp v214, v213, v213 row_shr:1 row_mask:0xf bank_mask:0xf
	v_mov_b32_dpp v164, v163 row_bcast:31 row_mask:0xc bank_mask:0xf
	v_max_f32_dpp v215, v215, v215 row_shr:4 row_mask:0xf bank_mask:0xf
	s_nop 1
	v_max_f32_dpp v215, v215, v215 row_shr:8 row_mask:0xf bank_mask:0xf
	s_nop 1
	v_max_f32_dpp v215, v215, v215 row_bcast:15 row_mask:0xa bank_mask:0xf
	s_nop 1
	v_max_f32_dpp v215, v215, v215 row_bcast:31 row_mask:0xc bank_mask:0xf
	v_max_f32_e64 v216, s44, s44
	v_readlane_b32 s0, v215, 63
	s_nop 1
	v_max_f32_e64 v215, s0, s0
	v_max_f32_e32 v215, v216, v215
	s_nop 0
	v_readfirstlane_b32 s33, v215
	s_nop 1
	v_mov_b32_e32 v215, s33
	v_sub_f32_e32 v215, s44, v215
	v_exp_f32_e32 v216, v215
	v_subrev_f32_e32 v212, s33, v212
	v_exp_f32_e32 v212, v212
	v_mul_f32_e32 v215, v84, v216
	s_nop 0
	v_readfirstlane_b32 s44, v215
	v_add_f32_dpp v217, v212, v212 row_shr:1 row_mask:0xf bank_mask:0xf bound_ctrl:1
	s_nop 0
	v_max_f32_dpp v214, v214, v214 row_shr:2 row_mask:0xf bank_mask:0xf
	v_add_f32_dpp v217, v217, v217 row_shr:2 row_mask:0xf bank_mask:0xf bound_ctrl:1
	s_nop 0
	v_max_f32_dpp v214, v214, v214 row_shr:4 row_mask:0xf bank_mask:0xf
	v_add_f32_dpp v217, v217, v217 row_shr:4 row_mask:0xf bank_mask:0xf bound_ctrl:1
	s_nop 0
	v_max_f32_dpp v214, v214, v214 row_shr:8 row_mask:0xf bank_mask:0xf
	v_add_f32_dpp v217, v217, v217 row_shr:8 row_mask:0xf bank_mask:0xf bound_ctrl:1
	v_pk_mul_f32 v[74:75], v[74:75], v[216:217] op_sel_hi:[1,0]
	v_max_f32_dpp v214, v214, v214 row_bcast:15 row_mask:0xa bank_mask:0xf
	v_pk_mul_f32 v[76:77], v[76:77], v[216:217] op_sel_hi:[1,0]
	v_mov_b32_dpp v218, v217 row_bcast:15 row_mask:0xa bank_mask:0xf
	v_max_f32_dpp v214, v214, v214 row_bcast:31 row_mask:0xc bank_mask:0xf
	v_max_f32_e64 v215, s6, s6
	v_readlane_b32 s0, v214, 63
	v_add_f32_e32 v165, v217, v218
	v_mov_b32_e32 v217, 0
	v_max_f32_e64 v214, s0, s0
	v_max_f32_e32 v214, v215, v214
	v_mov_b32_dpp v166, v165 row_bcast:31 row_mask:0xc bank_mask:0xf
	v_readfirstlane_b32 s43, v214
	s_mov_b64 s[0:1], -1
	s_nop 0
	v_subrev_f32_e32 v213, s43, v213
	v_exp_f32_e32 v213, v213
	v_mov_b32_e32 v214, s43
	v_sub_f32_e32 v214, s6, v214
	v_exp_f32_e32 v214, v214
	v_add_f32_dpp v216, v213, v213 row_shr:1 row_mask:0xf bank_mask:0xf bound_ctrl:1
	ds_write_b128 v137, v[210:213] offset:16400
	s_waitcnt lgkmcnt(0)
	v_mul_f32_e32 v215, v85, v214
	v_add_f32_dpp v216, v216, v216 row_shr:2 row_mask:0xf bank_mask:0xf bound_ctrl:1
	v_readfirstlane_b32 s45, v215
	s_nop 0
	v_add_f32_dpp v216, v216, v216 row_shr:4 row_mask:0xf bank_mask:0xf bound_ctrl:1
	v_pk_mul_f32 v[70:71], v[70:71], v[214:215] op_sel_hi:[1,0]
	v_pk_mul_f32 v[72:73], v[72:73], v[214:215] op_sel_hi:[1,0]
	v_add_f32_dpp v216, v216, v216 row_shr:8 row_mask:0xf bank_mask:0xf bound_ctrl:1
	s_nop 0
	s_nop 0
	v_mov_b32_dpp v217, v216 row_bcast:15 row_mask:0xa bank_mask:0xf
	v_add_f32_e32 v167, v216, v217
	s_nop 1
	v_mov_b32_dpp v168, v167 row_bcast:31 row_mask:0xc bank_mask:0xf
